# dil/SWA band item loops: waves 4-7 (second wave of each SIMD) run at s_setprio 1 to de-phase the two waves' MFMA and softmax sections; priority reset to 0 at the grid barrier
# baseline (speedup 1.0000x reference)
; #define LAS __attribute__((address_space(3)))
; __device__ __forceinline__ void dil_attn_phase(const Params& p, int half, LAS unsigned char* lds) {
;     const bf16_t* PROJ = (const bf16_t*)(p.ws + WS_PROJ); bf16_t* OG = (bf16_t*)(p.ws + WS_OG); float* LSE = (float*)(p.ws + WS_LSE);
;     (void)half;
;     for (int it = blockIdx.x; it < 1536; it += gridDim.x) {
;         const int g = it >> 9, rem = it & 511, bl = rem >> 8, rest = rem & 255, h = rest & 7, cr = rest >> 3;
;         const int r = g == 0 ? 1 : (g == 1 ? 4 : 16), L = SEQ / r, pr = cr % r, qc = cr / r;
;         const size_t tok0 = (size_t)bl * SEQ + pr;
;         band_item<128, 128, 64, 0>(PROJ + g * 1024 + h * 128, PROJ + 3072 + g * 1024 + h * 128, PROJ + 6144 + h * 128, 8192, tok0, r, L, qc * 256, 0.f,
;                                    OG + (size_t)g * 16384 * DM + h * 128, DM, LSE + (size_t)g * 16384 * 8 + h, nullptr, lds);
;     }
.LBB0_84:
	v_readfirstlane_b32 s26, v207
	s_cmpk_lt_u32 s26, 0x100
	s_cbranch_scc1 .Lbp_dil
	s_setprio 1

; #define LAS __attribute__((address_space(3)))
; __device__ __forceinline__ void swa_attn_phase(const Params& p, LAS unsigned char* lds) {
;     const bf16_t* PROJ = (const bf16_t*)(p.ws + WS_PROJ); bf16_t* Y = (bf16_t*)(p.ws + WS_H);
;     for (int it = blockIdx.x; it < 2048; it += gridDim.x) {
;         const int h = it & 15, rest = it >> 4, qc = rest & 31, b = rest >> 5;
;         band_item<64, 64, 128, 1>(PROJ + h * 64, PROJ + 1024 + (h >> 2) * 64, PROJ + 1280 + (h >> 2) * 64, 2560, (size_t)b * SEQ, 1, SEQ, qc * 256, p.swa_sink[h] * LOG2E,
;                                   Y + h * 64, DM, nullptr, PROJ + 1536 + h * 64, lds);
;     }
.LBB0_158:
	v_readfirstlane_b32 s23, v207
	s_cmpk_lt_u32 s23, 0x100
	s_cbranch_scc1 .Lbp_swa
	s_setprio 1

; __device__ __forceinline__ void xcd_barrier(const XcdBarrier& b) {
;     ...
;     }
;     __syncthreads();
.LBB0_529:
	s_or_b64 exec, exec, s[14:15]
	s_mov_b64 s[14:15], 0
	s_waitcnt lgkmcnt(0)
	s_setprio 0
	s_barrier
